# k21: packed f32 mul/fma in the scan's elementwise (E) role waves split into scalar halves
# speedup vs baseline: 1.0043x; 1.0043x over previous
.LBB0_727:
	v_cndmask_b32_e64 v28, 0, 1, s[14:15]
	v_cmp_ne_u32_e64 s[8:9], 1, v28
	s_andn2_b64 vcc, exec, s[14:15]
	s_cbranch_vccnz .LBB0_731
	v_lshlrev_b32_e32 v28, 16, v69
	v_add_f32_e32 v28, 0, v28
	v_lshlrev_b32_e32 v30, 16, v70
	v_add_f32_e32 v28, v28, v30
	v_lshlrev_b32_e32 v30, 16, v71
	v_add_f32_e32 v28, v28, v30
	v_lshlrev_b32_e32 v30, 16, v72
	v_add_f32_e32 v28, v28, v30
	v_lshlrev_b32_e32 v30, 16, v29
	v_add_f32_e32 v28, v28, v30
	v_lshlrev_b32_e32 v30, 16, v42
	v_add_f32_e32 v28, v28, v30
	v_lshlrev_b32_e32 v30, 16, v43
	v_add_f32_e32 v28, v28, v30
	v_lshlrev_b32_e32 v30, 16, v44
	v_add_f32_e32 v28, v28, v30
	v_lshlrev_b32_e32 v30, 16, v45
	v_add_f32_e32 v28, v28, v30
	v_lshlrev_b32_e32 v30, 16, v46
	v_add_f32_e32 v28, v28, v30
	v_lshlrev_b32_e32 v30, 16, v47
	v_add_f32_e32 v28, v28, v30
	v_lshlrev_b32_e32 v30, 16, v48
	v_add_f32_e32 v30, v28, v30
	v_lshlrev_b32_e32 v28, 16, v49
	v_add_f32_e32 v31, v30, v28
	v_lshlrev_b32_e32 v28, 16, v50
	v_add_f32_e32 v40, v31, v28
	v_lshlrev_b32_e32 v28, 16, v51
	v_exp_f32_e32 v101, v31
	v_cvt_f32_u32_e32 v37, v1
	v_cvt_f32_u32_e32 v36, v8
	v_add_f32_e32 v109, v40, v28
	v_lshlrev_b32_e32 v28, 16, v52
	v_add_f32_e32 v28, v109, v28
	v_exp_f32_e32 v28, v28
	v_exp_f32_e32 v41, v30
	v_lshlrev_b32_e32 v32, 16, v59
	v_exp_f32_e32 v111, v40
	v_exp_f32_e32 v120, v109
	v_lshlrev_b32_e32 v35, 16, v13
	v_lshlrev_b32_e32 v34, 16, v12
	v_mul_f32_e32 v93, v101, v32
	v_mul_f32_e32 v32, s12, v36
	v_mul_f32_e32 v33, s12, v37
	v_fma_f32 v36, v36, s12, -1.0
	v_fma_f32 v37, v37, s12, -1.0
	v_cvt_f32_u32_e32 v117, v9
	v_cvt_f32_u32_e32 v116, v0
	v_mul_f32_e32 v38, v4, v34
	v_mul_f32_e32 v39, v5, v35
	v_fma_f32 v36, v6, v36, 1.0
	v_fma_f32 v37, v7, v37, 1.0
	v_mul_f32_e32 v38, v38, v2
	v_mul_f32_e32 v39, v39, v3
	v_mul_f32_e32 v34, v36, v34
	v_mul_f32_e32 v35, v37, v35
	v_lshlrev_b32_e32 v37, 16, v65
	v_rcp_f32_e32 v30, v101
	v_mul_f32_e32 v95, v41, v38
	v_rcp_f32_e32 v31, v111
	v_lshlrev_b32_e32 v41, 16, v15
	v_lshlrev_b32_e32 v40, 16, v14
	v_rcp_f32_e32 v36, v120
	v_mul_f32_e32 v109, v120, v37
	v_rcp_f32_e32 v37, v28
	v_mul_f32_e32 v32, v32, v38
	v_mul_f32_e32 v33, v33, v39
	v_mul_f32_e32 v101, v101, v39
	v_mul_f32_e32 v38, s12, v116
	v_mul_f32_e32 v39, s12, v117
	v_mul_f32_e32 v112, v4, v40
	v_mul_f32_e32 v113, v5, v41
	v_fma_f32 v116, v116, s12, -1.0
	v_fma_f32 v117, v117, s12, -1.0
	v_mul_f32_e32 v118, v112, v10
	v_mul_f32_e32 v119, v113, v11
	v_fma_f32 v116, v6, v116, 1.0
	v_fma_f32 v117, v7, v117, 1.0
	s_and_b32 s4, s13, 2
	v_lshlrev_b32_e32 v102, 16, v62
	v_lshlrev_b32_e32 v121, 16, v68
	v_mul_f32_e32 v38, v38, v118
	v_mul_f32_e32 v39, v39, v119
	v_mul_f32_e32 v40, v116, v40
	v_mul_f32_e32 v41, v117, v41
	s_mulk_i32 s4, 0x5f00
	v_mul_f32_e32 v97, v30, v32
	v_mul_f32_e32 v99, v30, v34
	v_mul_f32_e32 v102, v111, v102
	v_mul_f32_e32 v103, v31, v33
	v_mul_f32_e32 v105, v31, v35
	v_mul_f32_e32 v111, v111, v118
	v_mul_f32_e32 v113, v36, v38
	v_mul_f32_e32 v115, v36, v40
	v_mul_f32_e32 v117, v120, v119
	v_mul_f32_e32 v118, v28, v121
	v_mul_f32_e32 v119, v37, v39
	v_mul_f32_e32 v121, v37, v41
	s_add_i32 s14, s4, 0
	v_mov_b32_dpp v94, v93 quad_perm:[1,1,3,3] row_mask:0xf bank_mask:0xf bound_ctrl:1
	v_mov_b32_dpp v96, v95 quad_perm:[1,1,3,3] row_mask:0xf bank_mask:0xf bound_ctrl:1
	v_mov_b32_dpp v98, v97 quad_perm:[1,1,3,3] row_mask:0xf bank_mask:0xf bound_ctrl:1
	v_mov_b32_dpp v100, v99 quad_perm:[1,1,3,3] row_mask:0xf bank_mask:0xf bound_ctrl:1
	v_mov_b32_dpp v104, v101 quad_perm:[1,1,3,3] row_mask:0xf bank_mask:0xf bound_ctrl:1
	v_mov_b32_dpp v106, v102 quad_perm:[1,1,3,3] row_mask:0xf bank_mask:0xf bound_ctrl:1
	v_mov_b32_dpp v107, v103 quad_perm:[1,1,3,3] row_mask:0xf bank_mask:0xf bound_ctrl:1
	v_mov_b32_dpp v108, v105 quad_perm:[1,1,3,3] row_mask:0xf bank_mask:0xf bound_ctrl:1
	v_mov_b32_dpp v110, v109 quad_perm:[1,1,3,3] row_mask:0xf bank_mask:0xf bound_ctrl:1
	v_mov_b32_dpp v112, v111 quad_perm:[1,1,3,3] row_mask:0xf bank_mask:0xf bound_ctrl:1
	v_mov_b32_dpp v114, v113 quad_perm:[1,1,3,3] row_mask:0xf bank_mask:0xf bound_ctrl:1
	v_mov_b32_dpp v116, v115 quad_perm:[1,1,3,3] row_mask:0xf bank_mask:0xf bound_ctrl:1
	v_mov_b32_dpp v120, v117 quad_perm:[1,1,3,3] row_mask:0xf bank_mask:0xf bound_ctrl:1
	v_mov_b32_dpp v122, v118 quad_perm:[1,1,3,3] row_mask:0xf bank_mask:0xf bound_ctrl:1
	v_mov_b32_dpp v123, v119 quad_perm:[1,1,3,3] row_mask:0xf bank_mask:0xf bound_ctrl:1
	v_mov_b32_dpp v124, v121 quad_perm:[1,1,3,3] row_mask:0xf bank_mask:0xf bound_ctrl:1
	s_and_saveexec_b64 s[4:5], s[6:7]
	s_cbranch_execz .LBB0_730
	v_cvt_pk_bf16_f32 v93, v93, v94
	v_cvt_pk_bf16_f32 v94, v95, v96
	v_lshl_add_u32 v95, v53, 1, s14
	v_cvt_pk_bf16_f32 v101, v101, v104
	v_add_u32_e32 v96, 0x400, v95
	v_cvt_pk_bf16_f32 v102, v102, v106
	ds_write2_b32 v96, v94, v101 offset0:176 offset1:212
	v_add_u32_e32 v94, 0xe00, v95
	v_cvt_pk_bf16_f32 v118, v118, v122
	v_cvt_pk_bf16_f32 v117, v117, v120
	v_cvt_pk_bf16_f32 v109, v109, v110
	v_cvt_pk_bf16_f32 v110, v111, v112
	v_cvt_pk_bf16_f32 v105, v105, v108
	v_cvt_pk_bf16_f32 v103, v103, v107
	v_cvt_pk_bf16_f32 v99, v99, v100
	v_cvt_pk_bf16_f32 v97, v97, v98
	ds_write2_b32 v94, v93, v102 offset0:112 offset1:148
	v_add_u32_e32 v93, 0x1800, v95
	v_add_u32_e32 v94, 0x2000, v95
	v_add_u32_e32 v96, 0x600, v95
	v_add_u32_e32 v95, 0x1000, v95
	v_cvt_pk_bf16_f32 v121, v121, v124
	v_cvt_pk_bf16_f32 v119, v119, v123
	v_cvt_pk_bf16_f32 v115, v115, v116
	v_cvt_pk_bf16_f32 v113, v113, v114
	ds_write2_b32 v93, v97, v103 offset0:48 offset1:84
	ds_write2_b32 v94, v99, v105 offset0:112 offset1:148
	ds_write2_b32 v96, v110, v117 offset0:120 offset1:156
	ds_write2_b32 v95, v109, v118 offset0:56 offset1:92
	ds_write2_b32 v93, v113, v119 offset0:120 offset1:156
	ds_write2_b32 v94, v115, v121 offset0:184 offset1:220
.LBB0_730:
	s_or_b64 exec, exec, s[4:5]
	v_mul_f32_e32 v36, v28, v36
	v_mul_f32_e32 v37, v28, v37
	v_mul_f32_e32 v30, v30, v28
	v_mul_f32_e32 v31, v31, v28
	v_mul_f32_e32 v40, v36, v40
	v_mul_f32_e32 v41, v37, v41
	v_mul_f32_e64 v36, v36, -v38
	v_mul_f32_e64 v37, v37, -v39
	v_mul_f32_e32 v34, v30, v34
	v_mul_f32_e32 v35, v31, v35
	v_mul_f32_e64 v30, v30, -v32
	v_mul_f32_e64 v31, v31, -v33
	v_add_u32_e32 v28, s14, v54
	v_cvt_pk_bf16_f32 v30, v30, v31
	v_cvt_pk_bf16_f32 v31, v36, v37
	v_cvt_pk_bf16_f32 v32, v34, v35
	v_cvt_pk_bf16_f32 v33, v40, v41
	v_add_u32_e32 v28, 0x2000, v28
	ds_write2_b64 v28, v[30:31], v[32:33] offset0:131 offset1:135
	v_lshl_or_b32 v30, v75, 16, v73
	v_lshl_or_b32 v31, v79, 16, v77
	v_add3_u32 v28, s14, v55, v56
	ds_write_b64 v28, v[30:31] offset:14360

.LBB0_733:
	s_and_b64 vcc, exec, s[8:9]
	s_cbranch_vccnz .LBB0_724
	v_lshlrev_b32_e32 v28, 16, v81
	v_add_f32_e32 v28, 0, v28
	v_lshlrev_b32_e32 v30, 16, v82
	v_add_f32_e32 v28, v28, v30
	v_lshlrev_b32_e32 v30, 16, v83
	v_add_f32_e32 v28, v28, v30
	v_lshlrev_b32_e32 v30, 16, v84
	v_add_f32_e32 v28, v28, v30
	v_lshlrev_b32_e32 v30, 16, v57
	v_add_f32_e32 v28, v28, v30
	v_lshlrev_b32_e32 v30, 16, v58
	v_add_f32_e32 v28, v28, v30
	v_lshlrev_b32_e32 v30, 16, v60
	v_add_f32_e32 v28, v28, v30
	v_lshlrev_b32_e32 v30, 16, v61
	v_add_f32_e32 v28, v28, v30
	v_lshlrev_b32_e32 v30, 16, v63
	v_add_f32_e32 v28, v28, v30
	v_lshlrev_b32_e32 v30, 16, v64
	v_add_f32_e32 v28, v28, v30
	v_lshlrev_b32_e32 v30, 16, v66
	v_add_f32_e32 v28, v28, v30
	v_lshlrev_b32_e32 v30, 16, v67
	v_add_f32_e32 v30, v28, v30
	v_lshlrev_b32_e32 v28, 16, v74
	v_add_f32_e32 v31, v30, v28
	v_lshlrev_b32_e32 v28, 16, v76
	v_add_f32_e32 v40, v31, v28
	v_lshlrev_b32_e32 v28, 16, v78
	v_exp_f32_e32 v101, v31
	v_cvt_f32_u32_e32 v37, v21
	v_cvt_f32_u32_e32 v36, v20
	v_add_f32_e32 v109, v40, v28
	v_lshlrev_b32_e32 v28, 16, v80
	v_add_f32_e32 v28, v109, v28
	v_exp_f32_e32 v28, v28
	v_exp_f32_e32 v41, v30
	v_lshlrev_b32_e32 v32, 16, v85
	v_exp_f32_e32 v111, v40
	v_exp_f32_e32 v120, v109
	v_lshlrev_b32_e32 v35, 16, v25
	v_lshlrev_b32_e32 v34, 16, v24
	v_mul_f32_e32 v93, v101, v32
	v_mul_f32_e32 v32, s12, v36
	v_mul_f32_e32 v33, s12, v37
	v_fma_f32 v36, v36, s12, -1.0
	v_fma_f32 v37, v37, s12, -1.0
	v_cvt_f32_u32_e32 v117, v23
	v_cvt_f32_u32_e32 v116, v22
	v_mul_f32_e32 v38, v4, v34
	v_mul_f32_e32 v39, v5, v35
	v_fma_f32 v36, v6, v36, 1.0
	v_fma_f32 v37, v7, v37, 1.0
	v_mul_f32_e32 v38, v16, v38
	v_mul_f32_e32 v39, v17, v39
	v_mul_f32_e32 v34, v36, v34
	v_mul_f32_e32 v35, v37, v35
	v_lshlrev_b32_e32 v37, 16, v87
	v_rcp_f32_e32 v30, v101
	v_mul_f32_e32 v95, v38, v41
	v_rcp_f32_e32 v31, v111
	v_lshlrev_b32_e32 v41, 16, v27
	v_lshlrev_b32_e32 v40, 16, v26
	v_rcp_f32_e32 v36, v120
	v_mul_f32_e32 v109, v120, v37
	v_rcp_f32_e32 v37, v28
	v_mul_f32_e32 v32, v32, v38
	v_mul_f32_e32 v33, v33, v39
	v_mul_f32_e32 v101, v39, v101
	v_mul_f32_e32 v38, s12, v116
	v_mul_f32_e32 v39, s12, v117
	v_mul_f32_e32 v112, v4, v40
	v_mul_f32_e32 v113, v5, v41
	v_fma_f32 v116, v116, s12, -1.0
	v_fma_f32 v117, v117, s12, -1.0
	v_mul_f32_e32 v118, v18, v112
	v_mul_f32_e32 v119, v19, v113
	v_fma_f32 v116, v6, v116, 1.0
	v_fma_f32 v117, v7, v117, 1.0
	s_and_b32 s4, s16, 3
	v_lshlrev_b32_e32 v102, 16, v86
	v_lshlrev_b32_e32 v121, 16, v88
	v_mul_f32_e32 v38, v38, v118
	v_mul_f32_e32 v39, v39, v119
	v_mul_f32_e32 v40, v116, v40
	v_mul_f32_e32 v41, v117, v41
	s_mulk_i32 s4, 0x5f00
	v_mul_f32_e32 v97, v32, v30
	v_mul_f32_e32 v99, v34, v30
	v_mul_f32_e32 v102, v111, v102
	v_mul_f32_e32 v103, v33, v31
	v_mul_f32_e32 v105, v35, v31
	v_mul_f32_e32 v111, v118, v111
	v_mul_f32_e32 v113, v38, v36
	v_mul_f32_e32 v115, v40, v36
	v_mul_f32_e32 v117, v119, v120
	v_mul_f32_e32 v118, v28, v121
	v_mul_f32_e32 v119, v39, v37
	v_mul_f32_e32 v121, v41, v37
	s_add_i32 s8, s4, 0
	v_mov_b32_dpp v94, v93 quad_perm:[1,1,3,3] row_mask:0xf bank_mask:0xf bound_ctrl:1
	v_mov_b32_dpp v96, v95 quad_perm:[1,1,3,3] row_mask:0xf bank_mask:0xf bound_ctrl:1
	v_mov_b32_dpp v98, v97 quad_perm:[1,1,3,3] row_mask:0xf bank_mask:0xf bound_ctrl:1
	v_mov_b32_dpp v100, v99 quad_perm:[1,1,3,3] row_mask:0xf bank_mask:0xf bound_ctrl:1
	v_mov_b32_dpp v104, v101 quad_perm:[1,1,3,3] row_mask:0xf bank_mask:0xf bound_ctrl:1
	v_mov_b32_dpp v106, v102 quad_perm:[1,1,3,3] row_mask:0xf bank_mask:0xf bound_ctrl:1
	v_mov_b32_dpp v107, v103 quad_perm:[1,1,3,3] row_mask:0xf bank_mask:0xf bound_ctrl:1
	v_mov_b32_dpp v108, v105 quad_perm:[1,1,3,3] row_mask:0xf bank_mask:0xf bound_ctrl:1
	v_mov_b32_dpp v110, v109 quad_perm:[1,1,3,3] row_mask:0xf bank_mask:0xf bound_ctrl:1
	v_mov_b32_dpp v112, v111 quad_perm:[1,1,3,3] row_mask:0xf bank_mask:0xf bound_ctrl:1
	v_mov_b32_dpp v114, v113 quad_perm:[1,1,3,3] row_mask:0xf bank_mask:0xf bound_ctrl:1
	v_mov_b32_dpp v116, v115 quad_perm:[1,1,3,3] row_mask:0xf bank_mask:0xf bound_ctrl:1
	v_mov_b32_dpp v120, v117 quad_perm:[1,1,3,3] row_mask:0xf bank_mask:0xf bound_ctrl:1
	v_mov_b32_dpp v122, v118 quad_perm:[1,1,3,3] row_mask:0xf bank_mask:0xf bound_ctrl:1
	v_mov_b32_dpp v123, v119 quad_perm:[1,1,3,3] row_mask:0xf bank_mask:0xf bound_ctrl:1
	v_mov_b32_dpp v124, v121 quad_perm:[1,1,3,3] row_mask:0xf bank_mask:0xf bound_ctrl:1
	s_and_saveexec_b64 s[4:5], s[6:7]
	s_cbranch_execz .LBB0_723
	v_cvt_pk_bf16_f32 v93, v93, v94
	v_cvt_pk_bf16_f32 v94, v95, v96
	v_lshl_add_u32 v95, v53, 1, s8
	v_cvt_pk_bf16_f32 v101, v101, v104
	v_add_u32_e32 v96, 0x400, v95
	v_cvt_pk_bf16_f32 v102, v102, v106
	ds_write2_b32 v96, v94, v101 offset0:176 offset1:212
	v_add_u32_e32 v94, 0xe00, v95
	v_cvt_pk_bf16_f32 v118, v118, v122
	v_cvt_pk_bf16_f32 v117, v117, v120
	v_cvt_pk_bf16_f32 v109, v109, v110
	v_cvt_pk_bf16_f32 v110, v111, v112
	v_cvt_pk_bf16_f32 v105, v105, v108
	v_cvt_pk_bf16_f32 v103, v103, v107
	v_cvt_pk_bf16_f32 v99, v99, v100
	v_cvt_pk_bf16_f32 v97, v97, v98
	ds_write2_b32 v94, v93, v102 offset0:112 offset1:148
	v_add_u32_e32 v93, 0x1800, v95
	v_add_u32_e32 v94, 0x2000, v95
	v_add_u32_e32 v96, 0x600, v95
	v_add_u32_e32 v95, 0x1000, v95
	v_cvt_pk_bf16_f32 v121, v121, v124
	v_cvt_pk_bf16_f32 v119, v119, v123
	v_cvt_pk_bf16_f32 v115, v115, v116
	v_cvt_pk_bf16_f32 v113, v113, v114
	ds_write2_b32 v93, v97, v103 offset0:48 offset1:84
	ds_write2_b32 v94, v99, v105 offset0:112 offset1:148
	ds_write2_b32 v96, v110, v117 offset0:120 offset1:156
	ds_write2_b32 v95, v109, v118 offset0:56 offset1:92
	ds_write2_b32 v93, v113, v119 offset0:120 offset1:156
	ds_write2_b32 v94, v115, v121 offset0:184 offset1:220
	s_branch .LBB0_723

.LBB0_744:
	v_cndmask_b32_e64 v28, 0, 1, s[14:15]
	v_cmp_ne_u32_e64 s[8:9], 1, v28
	s_andn2_b64 vcc, exec, s[14:15]
	s_cbranch_vccnz .LBB0_748
	v_lshlrev_b32_e32 v28, 16, v68
	v_add_f32_e32 v28, 0, v28
	v_lshlrev_b32_e32 v29, 16, v69
	v_add_f32_e32 v28, v28, v29
	v_lshlrev_b32_e32 v29, 16, v70
	v_add_f32_e32 v28, v28, v29
	v_lshlrev_b32_e32 v29, 16, v71
	v_add_f32_e32 v28, v28, v29
	v_lshlrev_b32_e32 v29, 16, v40
	v_add_f32_e32 v28, v28, v29
	v_lshlrev_b32_e32 v29, 16, v41
	v_add_f32_e32 v28, v28, v29
	v_lshlrev_b32_e32 v29, 16, v42
	v_add_f32_e32 v28, v28, v29
	v_lshlrev_b32_e32 v29, 16, v43
	v_add_f32_e32 v28, v28, v29
	v_lshlrev_b32_e32 v29, 16, v44
	v_add_f32_e32 v29, v28, v29
	v_exp_f32_e32 v39, v28
	v_lshlrev_b32_e32 v30, 16, v45
	v_lshlrev_b32_e32 v33, 16, v13
	v_exp_f32_e32 v101, v29
	v_lshlrev_b32_e32 v32, 16, v12
	v_cvt_f32_u32_e32 v35, v1
	v_cvt_f32_u32_e32 v34, v8
	v_add_f32_e32 v38, v29, v30
	v_lshlrev_b32_e32 v30, 16, v46
	v_mul_f32_e32 v36, v4, v32
	v_mul_f32_e32 v37, v5, v33
	v_cvt_f32_u32_e32 v117, v9
	v_cvt_f32_u32_e32 v116, v0
	v_add_f32_e32 v109, v38, v30
	v_lshlrev_b32_e32 v30, 16, v47
	v_mul_f32_e32 v36, v36, v2
	v_mul_f32_e32 v37, v37, v3
	v_exp_f32_e32 v111, v38
	v_add_f32_e32 v92, v109, v30
	v_lshlrev_b32_e32 v30, 16, v58
	v_mul_f32_e32 v95, v39, v36
	v_lshlrev_b32_e32 v39, 16, v15
	v_lshlrev_b32_e32 v38, 16, v14
	v_mul_f32_e32 v93, v101, v30
	v_mul_f32_e32 v30, s12, v34
	v_mul_f32_e32 v31, s12, v35
	v_mul_f32_e32 v112, v4, v38
	v_mul_f32_e32 v113, v5, v39
	v_rcp_f32_e32 v28, v101
	v_lshlrev_b32_e32 v102, 16, v61
	v_mul_f32_e32 v30, v30, v36
	v_mul_f32_e32 v31, v31, v37
	v_mul_f32_e32 v101, v101, v37
	v_mul_f32_e32 v36, s12, v116
	v_mul_f32_e32 v37, s12, v117
	v_mul_f32_e32 v118, v112, v10
	v_mul_f32_e32 v119, v113, v11
	v_rcp_f32_e32 v29, v111
	v_mul_f32_e32 v102, v111, v102
	v_exp_f32_e32 v120, v109
	v_mul_f32_e32 v111, v111, v118
	v_mul_f32_e32 v36, v36, v118
	v_mul_f32_e32 v37, v37, v119
	v_exp_f32_e32 v118, v92
	v_fma_f32 v34, v34, s12, -1.0
	v_fma_f32 v35, v35, s12, -1.0
	v_fma_f32 v116, v116, s12, -1.0
	v_fma_f32 v117, v117, s12, -1.0
	v_fma_f32 v34, v6, v34, 1.0
	v_fma_f32 v35, v7, v35, 1.0
	v_fma_f32 v116, v6, v116, 1.0
	v_fma_f32 v117, v7, v117, 1.0
	v_mul_f32_e32 v32, v34, v32
	v_mul_f32_e32 v33, v35, v33
	v_lshlrev_b32_e32 v35, 16, v64
	v_rcp_f32_e32 v34, v120
	v_mul_f32_e32 v109, v120, v35
	v_rcp_f32_e32 v35, v118
	s_and_b32 s4, s13, 2
	v_lshlrev_b32_e32 v121, 16, v67
	v_mul_f32_e32 v38, v116, v38
	v_mul_f32_e32 v39, v117, v39
	s_mulk_i32 s4, 0x5f00
	v_mul_f32_e32 v97, v28, v30
	v_mul_f32_e32 v99, v28, v32
	v_mul_f32_e32 v103, v29, v31
	v_mul_f32_e32 v105, v29, v33
	v_mul_f32_e32 v113, v34, v36
	v_mul_f32_e32 v115, v34, v38
	v_mul_f32_e32 v117, v120, v119
	v_mul_f32_e32 v118, v118, v121
	v_mul_f32_e32 v119, v35, v37
	v_mul_f32_e32 v121, v35, v39
	s_add_i32 s14, s4, 0
	v_mov_b32_dpp v94, v93 quad_perm:[1,1,3,3] row_mask:0xf bank_mask:0xf bound_ctrl:1
	v_mov_b32_dpp v96, v95 quad_perm:[1,1,3,3] row_mask:0xf bank_mask:0xf bound_ctrl:1
	v_mov_b32_dpp v98, v97 quad_perm:[1,1,3,3] row_mask:0xf bank_mask:0xf bound_ctrl:1
	v_mov_b32_dpp v100, v99 quad_perm:[1,1,3,3] row_mask:0xf bank_mask:0xf bound_ctrl:1
	v_mov_b32_dpp v104, v101 quad_perm:[1,1,3,3] row_mask:0xf bank_mask:0xf bound_ctrl:1
	v_mov_b32_dpp v106, v102 quad_perm:[1,1,3,3] row_mask:0xf bank_mask:0xf bound_ctrl:1
	v_mov_b32_dpp v107, v103 quad_perm:[1,1,3,3] row_mask:0xf bank_mask:0xf bound_ctrl:1
	v_mov_b32_dpp v108, v105 quad_perm:[1,1,3,3] row_mask:0xf bank_mask:0xf bound_ctrl:1
	v_mov_b32_dpp v110, v109 quad_perm:[1,1,3,3] row_mask:0xf bank_mask:0xf bound_ctrl:1
	v_mov_b32_dpp v112, v111 quad_perm:[1,1,3,3] row_mask:0xf bank_mask:0xf bound_ctrl:1
	v_mov_b32_dpp v114, v113 quad_perm:[1,1,3,3] row_mask:0xf bank_mask:0xf bound_ctrl:1
	v_mov_b32_dpp v116, v115 quad_perm:[1,1,3,3] row_mask:0xf bank_mask:0xf bound_ctrl:1
	v_mov_b32_dpp v120, v117 quad_perm:[1,1,3,3] row_mask:0xf bank_mask:0xf bound_ctrl:1
	v_mov_b32_dpp v122, v118 quad_perm:[1,1,3,3] row_mask:0xf bank_mask:0xf bound_ctrl:1
	v_mov_b32_dpp v123, v119 quad_perm:[1,1,3,3] row_mask:0xf bank_mask:0xf bound_ctrl:1
	v_mov_b32_dpp v124, v121 quad_perm:[1,1,3,3] row_mask:0xf bank_mask:0xf bound_ctrl:1
	s_and_saveexec_b64 s[4:5], s[6:7]
	s_cbranch_execz .LBB0_747
	v_cvt_pk_bf16_f32 v93, v93, v94
	v_cvt_pk_bf16_f32 v94, v95, v96
	v_lshl_add_u32 v95, v52, 1, s14
	v_cvt_pk_bf16_f32 v101, v101, v104
	v_add_u32_e32 v96, 0x400, v95
	v_cvt_pk_bf16_f32 v102, v102, v106
	ds_write2_b32 v96, v94, v101 offset0:32 offset1:68
	v_add_u32_e32 v94, 0xc00, v95
	v_cvt_pk_bf16_f32 v103, v103, v107
	v_cvt_pk_bf16_f32 v97, v97, v98
	ds_write2_b32 v94, v93, v102 offset0:96 offset1:132
	v_add_u32_e32 v93, 0x1400, v95
	v_cvt_pk_bf16_f32 v105, v105, v108
	v_cvt_pk_bf16_f32 v99, v99, v100
	ds_write2_b32 v93, v97, v103 offset0:160 offset1:196
	v_add_u32_e32 v93, 0x1e00, v95
	v_cvt_pk_bf16_f32 v119, v119, v123
	v_cvt_pk_bf16_f32 v118, v118, v122
	v_cvt_pk_bf16_f32 v117, v117, v120
	v_cvt_pk_bf16_f32 v113, v113, v114
	v_cvt_pk_bf16_f32 v109, v109, v110
	v_cvt_pk_bf16_f32 v110, v111, v112
	ds_write2_b32 v93, v99, v105 offset0:96 offset1:132
	ds_write2_b32 v96, v110, v117 offset0:104 offset1:140
	ds_write2_b32 v94, v109, v118 offset0:168 offset1:204
	v_add_u32_e32 v93, 0x1600, v95
	v_cvt_pk_bf16_f32 v121, v121, v124
	v_cvt_pk_bf16_f32 v115, v115, v116
	ds_write2_b32 v93, v113, v119 offset0:104 offset1:140
	v_add_u32_e32 v93, 0x2000, v95
	ds_write2_b32 v93, v115, v121 offset0:40 offset1:76
.LBB0_747:
	s_or_b64 exec, exec, s[4:5]
	v_lshlrev_b32_e32 v93, 16, v48
	v_add_f32_e32 v92, v92, v93
	v_lshlrev_b32_e32 v93, 16, v49
	v_add_f32_e32 v92, v92, v93
	v_lshlrev_b32_e32 v93, 16, v50
	v_add_f32_e32 v92, v92, v93
	v_lshlrev_b32_e32 v93, 16, v51
	v_add_f32_e32 v92, v92, v93
	v_exp_f32_e32 v92, v92
	s_nop 0
	v_mul_f32_e32 v34, v34, v92
	v_mul_f32_e32 v35, v35, v92
	v_mul_f32_e32 v28, v28, v92
	v_mul_f32_e32 v29, v29, v92
	v_mul_f32_e32 v38, v34, v38
	v_mul_f32_e32 v39, v35, v39
	v_mul_f32_e64 v34, v34, -v36
	v_mul_f32_e64 v35, v35, -v37
	v_mul_f32_e32 v32, v28, v32
	v_mul_f32_e32 v33, v29, v33
	v_mul_f32_e64 v28, v28, -v30
	v_mul_f32_e64 v29, v29, -v31
	v_add_u32_e32 v36, s14, v53
	v_cvt_pk_bf16_f32 v28, v28, v29
	v_cvt_pk_bf16_f32 v29, v34, v35
	v_cvt_pk_bf16_f32 v30, v32, v33
	v_cvt_pk_bf16_f32 v31, v38, v39
	v_add_u32_e32 v32, 0x2000, v36
	ds_write2_b64 v32, v[28:29], v[30:31] offset0:129 offset1:133
	v_lshl_or_b32 v28, v74, 16, v72
	v_lshl_or_b32 v29, v78, 16, v76
	v_add3_u32 v30, s14, v54, v55
	ds_write_b64 v30, v[28:29] offset:14344

.LBB0_750:
	s_and_b64 vcc, exec, s[8:9]
	s_cbranch_vccnz .LBB0_741
	v_lshlrev_b32_e32 v28, 16, v80
	v_add_f32_e32 v28, 0, v28
	v_lshlrev_b32_e32 v29, 16, v81
	v_add_f32_e32 v28, v28, v29
	v_lshlrev_b32_e32 v29, 16, v82
	v_add_f32_e32 v28, v28, v29
	v_lshlrev_b32_e32 v29, 16, v83
	v_add_f32_e32 v28, v28, v29
	v_lshlrev_b32_e32 v29, 16, v56
	v_add_f32_e32 v28, v28, v29
	v_lshlrev_b32_e32 v29, 16, v57
	v_add_f32_e32 v28, v28, v29
	v_lshlrev_b32_e32 v29, 16, v59
	v_add_f32_e32 v28, v28, v29
	v_lshlrev_b32_e32 v29, 16, v60
	v_add_f32_e32 v28, v28, v29
	v_lshlrev_b32_e32 v29, 16, v62
	v_add_f32_e32 v29, v28, v29
	v_exp_f32_e32 v39, v28
	v_lshlrev_b32_e32 v30, 16, v63
	v_lshlrev_b32_e32 v33, 16, v25
	v_exp_f32_e32 v101, v29
	v_lshlrev_b32_e32 v32, 16, v24
	v_cvt_f32_u32_e32 v35, v21
	v_cvt_f32_u32_e32 v34, v20
	v_add_f32_e32 v38, v29, v30
	v_lshlrev_b32_e32 v30, 16, v65
	v_mul_f32_e32 v36, v4, v32
	v_mul_f32_e32 v37, v5, v33
	v_cvt_f32_u32_e32 v117, v23
	v_cvt_f32_u32_e32 v116, v22
	v_add_f32_e32 v109, v38, v30
	v_lshlrev_b32_e32 v30, 16, v66
	v_mul_f32_e32 v36, v16, v36
	v_mul_f32_e32 v37, v17, v37
	v_exp_f32_e32 v111, v38
	v_add_f32_e32 v92, v109, v30
	v_lshlrev_b32_e32 v30, 16, v84
	v_mul_f32_e32 v95, v36, v39
	v_lshlrev_b32_e32 v39, 16, v27
	v_lshlrev_b32_e32 v38, 16, v26
	v_mul_f32_e32 v93, v101, v30
	v_mul_f32_e32 v30, s12, v34
	v_mul_f32_e32 v31, s12, v35
	v_mul_f32_e32 v112, v4, v38
	v_mul_f32_e32 v113, v5, v39
	v_rcp_f32_e32 v28, v101
	v_lshlrev_b32_e32 v102, 16, v85
	v_mul_f32_e32 v30, v30, v36
	v_mul_f32_e32 v31, v31, v37
	v_mul_f32_e32 v101, v37, v101
	v_mul_f32_e32 v36, s12, v116
	v_mul_f32_e32 v37, s12, v117
	v_mul_f32_e32 v118, v18, v112
	v_mul_f32_e32 v119, v19, v113
	v_rcp_f32_e32 v29, v111
	v_mul_f32_e32 v102, v111, v102
	v_exp_f32_e32 v120, v109
	v_mul_f32_e32 v111, v118, v111
	v_mul_f32_e32 v36, v36, v118
	v_mul_f32_e32 v37, v37, v119
	v_exp_f32_e32 v118, v92
	v_fma_f32 v34, v34, s12, -1.0
	v_fma_f32 v35, v35, s12, -1.0
	v_fma_f32 v116, v116, s12, -1.0
	v_fma_f32 v117, v117, s12, -1.0
	v_fma_f32 v34, v6, v34, 1.0
	v_fma_f32 v35, v7, v35, 1.0
	v_fma_f32 v116, v6, v116, 1.0
	v_fma_f32 v117, v7, v117, 1.0
	v_mul_f32_e32 v32, v34, v32
	v_mul_f32_e32 v33, v35, v33
	v_lshlrev_b32_e32 v35, 16, v86
	v_rcp_f32_e32 v34, v120
	v_mul_f32_e32 v109, v120, v35
	v_rcp_f32_e32 v35, v118
	s_and_b32 s4, s16, 3
	v_lshlrev_b32_e32 v121, 16, v87
	v_mul_f32_e32 v38, v116, v38
	v_mul_f32_e32 v39, v117, v39
	s_mulk_i32 s4, 0x5f00
	v_mul_f32_e32 v97, v30, v28
	v_mul_f32_e32 v99, v32, v28
	v_mul_f32_e32 v103, v31, v29
	v_mul_f32_e32 v105, v33, v29
	v_mul_f32_e32 v113, v36, v34
	v_mul_f32_e32 v115, v38, v34
	v_mul_f32_e32 v117, v119, v120
	v_mul_f32_e32 v118, v118, v121
	v_mul_f32_e32 v119, v37, v35
	v_mul_f32_e32 v121, v39, v35
	s_add_i32 s8, s4, 0
	v_mov_b32_dpp v94, v93 quad_perm:[1,1,3,3] row_mask:0xf bank_mask:0xf bound_ctrl:1
	v_mov_b32_dpp v96, v95 quad_perm:[1,1,3,3] row_mask:0xf bank_mask:0xf bound_ctrl:1
	v_mov_b32_dpp v98, v97 quad_perm:[1,1,3,3] row_mask:0xf bank_mask:0xf bound_ctrl:1
	v_mov_b32_dpp v100, v99 quad_perm:[1,1,3,3] row_mask:0xf bank_mask:0xf bound_ctrl:1
	v_mov_b32_dpp v104, v101 quad_perm:[1,1,3,3] row_mask:0xf bank_mask:0xf bound_ctrl:1
	v_mov_b32_dpp v106, v102 quad_perm:[1,1,3,3] row_mask:0xf bank_mask:0xf bound_ctrl:1
	v_mov_b32_dpp v107, v103 quad_perm:[1,1,3,3] row_mask:0xf bank_mask:0xf bound_ctrl:1
	v_mov_b32_dpp v108, v105 quad_perm:[1,1,3,3] row_mask:0xf bank_mask:0xf bound_ctrl:1
	v_mov_b32_dpp v110, v109 quad_perm:[1,1,3,3] row_mask:0xf bank_mask:0xf bound_ctrl:1
	v_mov_b32_dpp v112, v111 quad_perm:[1,1,3,3] row_mask:0xf bank_mask:0xf bound_ctrl:1
	v_mov_b32_dpp v114, v113 quad_perm:[1,1,3,3] row_mask:0xf bank_mask:0xf bound_ctrl:1
	v_mov_b32_dpp v116, v115 quad_perm:[1,1,3,3] row_mask:0xf bank_mask:0xf bound_ctrl:1
	v_mov_b32_dpp v120, v117 quad_perm:[1,1,3,3] row_mask:0xf bank_mask:0xf bound_ctrl:1
	v_mov_b32_dpp v122, v118 quad_perm:[1,1,3,3] row_mask:0xf bank_mask:0xf bound_ctrl:1
	v_mov_b32_dpp v123, v119 quad_perm:[1,1,3,3] row_mask:0xf bank_mask:0xf bound_ctrl:1
	v_mov_b32_dpp v124, v121 quad_perm:[1,1,3,3] row_mask:0xf bank_mask:0xf bound_ctrl:1
	s_and_saveexec_b64 s[4:5], s[6:7]
	s_cbranch_execz .LBB0_740
	v_cvt_pk_bf16_f32 v93, v93, v94
	v_cvt_pk_bf16_f32 v94, v95, v96
	v_lshl_add_u32 v95, v52, 1, s8
	v_cvt_pk_bf16_f32 v101, v101, v104
	v_add_u32_e32 v96, 0x400, v95
	v_cvt_pk_bf16_f32 v102, v102, v106
	ds_write2_b32 v96, v94, v101 offset0:32 offset1:68
	v_add_u32_e32 v94, 0xc00, v95
	v_cvt_pk_bf16_f32 v103, v103, v107
	v_cvt_pk_bf16_f32 v97, v97, v98
	ds_write2_b32 v94, v93, v102 offset0:96 offset1:132
	v_add_u32_e32 v93, 0x1400, v95
	v_cvt_pk_bf16_f32 v105, v105, v108
	v_cvt_pk_bf16_f32 v99, v99, v100
	ds_write2_b32 v93, v97, v103 offset0:160 offset1:196
	v_add_u32_e32 v93, 0x1e00, v95
	v_cvt_pk_bf16_f32 v119, v119, v123
	v_cvt_pk_bf16_f32 v118, v118, v122
	v_cvt_pk_bf16_f32 v117, v117, v120
	v_cvt_pk_bf16_f32 v113, v113, v114
	v_cvt_pk_bf16_f32 v109, v109, v110
	v_cvt_pk_bf16_f32 v110, v111, v112
	ds_write2_b32 v93, v99, v105 offset0:96 offset1:132
	ds_write2_b32 v96, v110, v117 offset0:104 offset1:140
	ds_write2_b32 v94, v109, v118 offset0:168 offset1:204
	v_add_u32_e32 v93, 0x1600, v95
	v_cvt_pk_bf16_f32 v121, v121, v124
	v_cvt_pk_bf16_f32 v115, v115, v116
	ds_write2_b32 v93, v113, v119 offset0:104 offset1:140
	v_add_u32_e32 v93, 0x2000, v95
	ds_write2_b32 v93, v115, v121 offset0:40 offset1:76
	s_branch .LBB0_740

.LBB0_760:
	v_cndmask_b32_e64 v28, 0, 1, s[14:15]
	v_cmp_ne_u32_e64 s[8:9], 1, v28
	s_andn2_b64 vcc, exec, s[14:15]
	s_cbranch_vccnz .LBB0_764
	v_lshlrev_b32_e32 v28, 16, v68
	v_add_f32_e32 v28, 0, v28
	v_lshlrev_b32_e32 v29, 16, v69
	v_add_f32_e32 v28, v28, v29
	v_lshlrev_b32_e32 v29, 16, v70
	v_add_f32_e32 v28, v28, v29
	v_lshlrev_b32_e32 v29, 16, v71
	v_add_f32_e32 v28, v28, v29
	v_lshlrev_b32_e32 v29, 16, v40
	v_add_f32_e32 v29, v28, v29
	v_exp_f32_e32 v39, v28
	v_lshlrev_b32_e32 v30, 16, v41
	v_lshlrev_b32_e32 v33, 16, v13
	v_exp_f32_e32 v101, v29
	v_lshlrev_b32_e32 v32, 16, v12
	v_cvt_f32_u32_e32 v35, v1
	v_cvt_f32_u32_e32 v34, v8
	v_add_f32_e32 v38, v29, v30
	v_lshlrev_b32_e32 v30, 16, v42
	v_mul_f32_e32 v36, v4, v32
	v_mul_f32_e32 v37, v5, v33
	v_cvt_f32_u32_e32 v117, v9
	v_cvt_f32_u32_e32 v116, v0
	v_add_f32_e32 v109, v38, v30
	v_lshlrev_b32_e32 v30, 16, v43
	v_mul_f32_e32 v36, v36, v2
	v_mul_f32_e32 v37, v37, v3
	v_exp_f32_e32 v111, v38
	v_add_f32_e32 v92, v109, v30
	v_lshlrev_b32_e32 v30, 16, v58
	v_mul_f32_e32 v95, v39, v36
	v_lshlrev_b32_e32 v39, 16, v15
	v_lshlrev_b32_e32 v38, 16, v14
	v_mul_f32_e32 v93, v101, v30
	v_mul_f32_e32 v30, s12, v34
	v_mul_f32_e32 v31, s12, v35
	v_mul_f32_e32 v112, v4, v38
	v_mul_f32_e32 v113, v5, v39
	v_rcp_f32_e32 v28, v101
	v_lshlrev_b32_e32 v102, 16, v61
	v_mul_f32_e32 v30, v30, v36
	v_mul_f32_e32 v31, v31, v37
	v_mul_f32_e32 v101, v101, v37
	v_mul_f32_e32 v36, s12, v116
	v_mul_f32_e32 v37, s12, v117
	v_mul_f32_e32 v118, v112, v10
	v_mul_f32_e32 v119, v113, v11
	v_rcp_f32_e32 v29, v111
	v_mul_f32_e32 v102, v111, v102
	v_exp_f32_e32 v120, v109
	v_mul_f32_e32 v111, v111, v118
	v_mul_f32_e32 v36, v36, v118
	v_mul_f32_e32 v37, v37, v119
	v_exp_f32_e32 v118, v92
	v_fma_f32 v34, v34, s12, -1.0
	v_fma_f32 v35, v35, s12, -1.0
	v_fma_f32 v116, v116, s12, -1.0
	v_fma_f32 v117, v117, s12, -1.0
	v_fma_f32 v34, v6, v34, 1.0
	v_fma_f32 v35, v7, v35, 1.0
	v_fma_f32 v116, v6, v116, 1.0
	v_fma_f32 v117, v7, v117, 1.0
	v_mul_f32_e32 v32, v34, v32
	v_mul_f32_e32 v33, v35, v33
	v_lshlrev_b32_e32 v35, 16, v64
	v_rcp_f32_e32 v34, v120
	v_mul_f32_e32 v109, v120, v35
	v_rcp_f32_e32 v35, v118
	s_and_b32 s4, s13, 2
	v_lshlrev_b32_e32 v121, 16, v67
	v_mul_f32_e32 v38, v116, v38
	v_mul_f32_e32 v39, v117, v39
	s_mulk_i32 s4, 0x5f00
	v_mul_f32_e32 v97, v28, v30
	v_mul_f32_e32 v99, v28, v32
	v_mul_f32_e32 v103, v29, v31
	v_mul_f32_e32 v105, v29, v33
	v_mul_f32_e32 v113, v34, v36
	v_mul_f32_e32 v115, v34, v38
	v_mul_f32_e32 v117, v120, v119
	v_mul_f32_e32 v118, v118, v121
	v_mul_f32_e32 v119, v35, v37
	v_mul_f32_e32 v121, v35, v39
	s_add_i32 s14, s4, 0
	v_mov_b32_dpp v94, v93 quad_perm:[1,1,3,3] row_mask:0xf bank_mask:0xf bound_ctrl:1
	v_mov_b32_dpp v96, v95 quad_perm:[1,1,3,3] row_mask:0xf bank_mask:0xf bound_ctrl:1
	v_mov_b32_dpp v98, v97 quad_perm:[1,1,3,3] row_mask:0xf bank_mask:0xf bound_ctrl:1
	v_mov_b32_dpp v100, v99 quad_perm:[1,1,3,3] row_mask:0xf bank_mask:0xf bound_ctrl:1
	v_mov_b32_dpp v104, v101 quad_perm:[1,1,3,3] row_mask:0xf bank_mask:0xf bound_ctrl:1
	v_mov_b32_dpp v106, v102 quad_perm:[1,1,3,3] row_mask:0xf bank_mask:0xf bound_ctrl:1
	v_mov_b32_dpp v107, v103 quad_perm:[1,1,3,3] row_mask:0xf bank_mask:0xf bound_ctrl:1
	v_mov_b32_dpp v108, v105 quad_perm:[1,1,3,3] row_mask:0xf bank_mask:0xf bound_ctrl:1
	v_mov_b32_dpp v110, v109 quad_perm:[1,1,3,3] row_mask:0xf bank_mask:0xf bound_ctrl:1
	v_mov_b32_dpp v112, v111 quad_perm:[1,1,3,3] row_mask:0xf bank_mask:0xf bound_ctrl:1
	v_mov_b32_dpp v114, v113 quad_perm:[1,1,3,3] row_mask:0xf bank_mask:0xf bound_ctrl:1
	v_mov_b32_dpp v116, v115 quad_perm:[1,1,3,3] row_mask:0xf bank_mask:0xf bound_ctrl:1
	v_mov_b32_dpp v120, v117 quad_perm:[1,1,3,3] row_mask:0xf bank_mask:0xf bound_ctrl:1
	v_mov_b32_dpp v122, v118 quad_perm:[1,1,3,3] row_mask:0xf bank_mask:0xf bound_ctrl:1
	v_mov_b32_dpp v123, v119 quad_perm:[1,1,3,3] row_mask:0xf bank_mask:0xf bound_ctrl:1
	v_mov_b32_dpp v124, v121 quad_perm:[1,1,3,3] row_mask:0xf bank_mask:0xf bound_ctrl:1
	s_and_saveexec_b64 s[4:5], s[6:7]
	s_cbranch_execz .LBB0_763
	v_cvt_pk_bf16_f32 v101, v101, v104
	v_cvt_pk_bf16_f32 v93, v93, v94
	v_cvt_pk_bf16_f32 v94, v95, v96
	v_lshl_add_u32 v95, v52, 1, s14
	v_cvt_pk_bf16_f32 v102, v102, v106
	ds_write2_b32 v95, v94, v101 offset0:144 offset1:180
	v_add_u32_e32 v94, 0x800, v95
	v_cvt_pk_bf16_f32 v105, v105, v108
	v_cvt_pk_bf16_f32 v103, v103, v107
	v_cvt_pk_bf16_f32 v99, v99, v100
	v_cvt_pk_bf16_f32 v97, v97, v98
	ds_write2_b32 v94, v93, v102 offset0:208 offset1:244
	v_add_u32_e32 v93, 0x1400, v95
	v_add_u32_e32 v94, 0x1c00, v95
	v_cvt_pk_bf16_f32 v118, v118, v122
	v_cvt_pk_bf16_f32 v117, v117, v120
	v_cvt_pk_bf16_f32 v109, v109, v110
	v_cvt_pk_bf16_f32 v110, v111, v112
	ds_write2_b32 v93, v97, v103 offset0:16 offset1:52
	ds_write2_b32 v94, v99, v105 offset0:80 offset1:116
	ds_write2_b32 v95, v110, v117 offset0:216 offset1:252
	v_add_u32_e32 v95, 0xc00, v95
	v_cvt_pk_bf16_f32 v121, v121, v124
	v_cvt_pk_bf16_f32 v119, v119, v123
	v_cvt_pk_bf16_f32 v115, v115, v116
	v_cvt_pk_bf16_f32 v113, v113, v114
	ds_write2_b32 v95, v109, v118 offset0:24 offset1:60
	ds_write2_b32 v93, v113, v119 offset0:88 offset1:124
	ds_write2_b32 v94, v115, v121 offset0:152 offset1:188
.LBB0_763:
	s_or_b64 exec, exec, s[4:5]
	v_lshlrev_b32_e32 v93, 16, v44
	v_add_f32_e32 v92, v92, v93
	v_lshlrev_b32_e32 v93, 16, v45
	v_add_f32_e32 v92, v92, v93
	v_lshlrev_b32_e32 v93, 16, v46
	v_add_f32_e32 v92, v92, v93
	v_lshlrev_b32_e32 v93, 16, v47
	v_add_f32_e32 v92, v92, v93
	v_lshlrev_b32_e32 v93, 16, v48
	v_add_f32_e32 v92, v92, v93
	v_lshlrev_b32_e32 v93, 16, v49
	v_add_f32_e32 v92, v92, v93
	v_lshlrev_b32_e32 v93, 16, v50
	v_add_f32_e32 v92, v92, v93
	v_lshlrev_b32_e32 v93, 16, v51
	v_add_f32_e32 v92, v92, v93
	v_exp_f32_e32 v92, v92
	s_nop 0
	v_mul_f32_e32 v34, v34, v92
	v_mul_f32_e32 v35, v35, v92
	v_mul_f32_e32 v28, v28, v92
	v_mul_f32_e32 v29, v29, v92
	v_mul_f32_e32 v38, v34, v38
	v_mul_f32_e32 v39, v35, v39
	v_mul_f32_e64 v34, v34, -v36
	v_mul_f32_e64 v35, v35, -v37
	v_mul_f32_e32 v32, v28, v32
	v_mul_f32_e32 v33, v29, v33
	v_mul_f32_e64 v28, v28, -v30
	v_mul_f32_e64 v29, v29, -v31
	v_add_u32_e32 v36, s14, v53
	v_cvt_pk_bf16_f32 v28, v28, v29
	v_cvt_pk_bf16_f32 v29, v34, v35
	v_cvt_pk_bf16_f32 v30, v32, v33
	v_cvt_pk_bf16_f32 v31, v38, v39
	v_add_u32_e32 v32, 0x2000, v36
	ds_write2_b64 v32, v[28:29], v[30:31] offset0:130 offset1:134
	v_lshl_or_b32 v28, v74, 16, v72
	v_lshl_or_b32 v29, v78, 16, v76
	v_add3_u32 v30, s14, v54, v55
	ds_write_b64 v30, v[28:29] offset:14352

.LBB0_766:
	s_and_b64 vcc, exec, s[8:9]
	s_cbranch_vccnz .LBB0_757
	v_lshlrev_b32_e32 v28, 16, v80
	v_add_f32_e32 v28, 0, v28
	v_lshlrev_b32_e32 v29, 16, v81
	v_add_f32_e32 v28, v28, v29
	v_lshlrev_b32_e32 v29, 16, v82
	v_add_f32_e32 v28, v28, v29
	v_lshlrev_b32_e32 v29, 16, v83
	v_add_f32_e32 v28, v28, v29
	v_lshlrev_b32_e32 v29, 16, v56
	v_add_f32_e32 v29, v28, v29
	v_exp_f32_e32 v39, v28
	v_lshlrev_b32_e32 v30, 16, v57
	v_lshlrev_b32_e32 v33, 16, v25
	v_exp_f32_e32 v101, v29
	v_lshlrev_b32_e32 v32, 16, v24
	v_cvt_f32_u32_e32 v35, v21
	v_cvt_f32_u32_e32 v34, v20
	v_add_f32_e32 v38, v29, v30
	v_lshlrev_b32_e32 v30, 16, v59
	v_mul_f32_e32 v36, v4, v32
	v_mul_f32_e32 v37, v5, v33
	v_cvt_f32_u32_e32 v117, v23
	v_cvt_f32_u32_e32 v116, v22
	v_add_f32_e32 v109, v38, v30
	v_lshlrev_b32_e32 v30, 16, v60
	v_mul_f32_e32 v36, v16, v36
	v_mul_f32_e32 v37, v17, v37
	v_exp_f32_e32 v111, v38
	v_add_f32_e32 v92, v109, v30
	v_lshlrev_b32_e32 v30, 16, v84
	v_mul_f32_e32 v95, v36, v39
	v_lshlrev_b32_e32 v39, 16, v27
	v_lshlrev_b32_e32 v38, 16, v26
	v_mul_f32_e32 v93, v101, v30
	v_mul_f32_e32 v30, s12, v34
	v_mul_f32_e32 v31, s12, v35
	v_mul_f32_e32 v112, v4, v38
	v_mul_f32_e32 v113, v5, v39
	v_rcp_f32_e32 v28, v101
	v_lshlrev_b32_e32 v102, 16, v85
	v_mul_f32_e32 v30, v30, v36
	v_mul_f32_e32 v31, v31, v37
	v_mul_f32_e32 v101, v37, v101
	v_mul_f32_e32 v36, s12, v116
	v_mul_f32_e32 v37, s12, v117
	v_mul_f32_e32 v118, v18, v112
	v_mul_f32_e32 v119, v19, v113
	v_rcp_f32_e32 v29, v111
	v_mul_f32_e32 v102, v111, v102
	v_exp_f32_e32 v120, v109
	v_mul_f32_e32 v111, v118, v111
	v_mul_f32_e32 v36, v36, v118
	v_mul_f32_e32 v37, v37, v119
	v_exp_f32_e32 v118, v92
	v_fma_f32 v34, v34, s12, -1.0
	v_fma_f32 v35, v35, s12, -1.0
	v_fma_f32 v116, v116, s12, -1.0
	v_fma_f32 v117, v117, s12, -1.0
	v_fma_f32 v34, v6, v34, 1.0
	v_fma_f32 v35, v7, v35, 1.0
	v_fma_f32 v116, v6, v116, 1.0
	v_fma_f32 v117, v7, v117, 1.0
	v_mul_f32_e32 v32, v34, v32
	v_mul_f32_e32 v33, v35, v33
	v_lshlrev_b32_e32 v35, 16, v86
	v_rcp_f32_e32 v34, v120
	v_mul_f32_e32 v109, v120, v35
	v_rcp_f32_e32 v35, v118
	s_and_b32 s4, s16, 3
	v_lshlrev_b32_e32 v121, 16, v87
	v_mul_f32_e32 v38, v116, v38
	v_mul_f32_e32 v39, v117, v39
	s_mulk_i32 s4, 0x5f00
	v_mul_f32_e32 v97, v30, v28
	v_mul_f32_e32 v99, v32, v28
	v_mul_f32_e32 v103, v31, v29
	v_mul_f32_e32 v105, v33, v29
	v_mul_f32_e32 v113, v36, v34
	v_mul_f32_e32 v115, v38, v34
	v_mul_f32_e32 v117, v119, v120
	v_mul_f32_e32 v118, v118, v121
	v_mul_f32_e32 v119, v37, v35
	v_mul_f32_e32 v121, v39, v35
	s_add_i32 s8, s4, 0
	v_mov_b32_dpp v94, v93 quad_perm:[1,1,3,3] row_mask:0xf bank_mask:0xf bound_ctrl:1
	v_mov_b32_dpp v96, v95 quad_perm:[1,1,3,3] row_mask:0xf bank_mask:0xf bound_ctrl:1
	v_mov_b32_dpp v98, v97 quad_perm:[1,1,3,3] row_mask:0xf bank_mask:0xf bound_ctrl:1
	v_mov_b32_dpp v100, v99 quad_perm:[1,1,3,3] row_mask:0xf bank_mask:0xf bound_ctrl:1
	v_mov_b32_dpp v104, v101 quad_perm:[1,1,3,3] row_mask:0xf bank_mask:0xf bound_ctrl:1
	v_mov_b32_dpp v106, v102 quad_perm:[1,1,3,3] row_mask:0xf bank_mask:0xf bound_ctrl:1
	v_mov_b32_dpp v107, v103 quad_perm:[1,1,3,3] row_mask:0xf bank_mask:0xf bound_ctrl:1
	v_mov_b32_dpp v108, v105 quad_perm:[1,1,3,3] row_mask:0xf bank_mask:0xf bound_ctrl:1
	v_mov_b32_dpp v110, v109 quad_perm:[1,1,3,3] row_mask:0xf bank_mask:0xf bound_ctrl:1
	v_mov_b32_dpp v112, v111 quad_perm:[1,1,3,3] row_mask:0xf bank_mask:0xf bound_ctrl:1
	v_mov_b32_dpp v114, v113 quad_perm:[1,1,3,3] row_mask:0xf bank_mask:0xf bound_ctrl:1
	v_mov_b32_dpp v116, v115 quad_perm:[1,1,3,3] row_mask:0xf bank_mask:0xf bound_ctrl:1
	v_mov_b32_dpp v120, v117 quad_perm:[1,1,3,3] row_mask:0xf bank_mask:0xf bound_ctrl:1
	v_mov_b32_dpp v122, v118 quad_perm:[1,1,3,3] row_mask:0xf bank_mask:0xf bound_ctrl:1
	v_mov_b32_dpp v123, v119 quad_perm:[1,1,3,3] row_mask:0xf bank_mask:0xf bound_ctrl:1
	v_mov_b32_dpp v124, v121 quad_perm:[1,1,3,3] row_mask:0xf bank_mask:0xf bound_ctrl:1
	s_and_saveexec_b64 s[4:5], s[6:7]
	s_cbranch_execz .LBB0_756
	v_cvt_pk_bf16_f32 v101, v101, v104
	v_cvt_pk_bf16_f32 v93, v93, v94
	v_cvt_pk_bf16_f32 v94, v95, v96
	v_lshl_add_u32 v95, v52, 1, s8
	v_cvt_pk_bf16_f32 v102, v102, v106
	ds_write2_b32 v95, v94, v101 offset0:144 offset1:180
	v_add_u32_e32 v94, 0x800, v95
	v_cvt_pk_bf16_f32 v105, v105, v108
	v_cvt_pk_bf16_f32 v103, v103, v107
	v_cvt_pk_bf16_f32 v99, v99, v100
	v_cvt_pk_bf16_f32 v97, v97, v98
	ds_write2_b32 v94, v93, v102 offset0:208 offset1:244
	v_add_u32_e32 v93, 0x1400, v95
	v_add_u32_e32 v94, 0x1c00, v95
	v_cvt_pk_bf16_f32 v118, v118, v122
	v_cvt_pk_bf16_f32 v117, v117, v120
	v_cvt_pk_bf16_f32 v109, v109, v110
	v_cvt_pk_bf16_f32 v110, v111, v112
	ds_write2_b32 v93, v97, v103 offset0:16 offset1:52
	ds_write2_b32 v94, v99, v105 offset0:80 offset1:116
	ds_write2_b32 v95, v110, v117 offset0:216 offset1:252
	v_add_u32_e32 v95, 0xc00, v95
	v_cvt_pk_bf16_f32 v121, v121, v124
	v_cvt_pk_bf16_f32 v119, v119, v123
	v_cvt_pk_bf16_f32 v115, v115, v116
	v_cvt_pk_bf16_f32 v113, v113, v114
	ds_write2_b32 v95, v109, v118 offset0:24 offset1:60
	ds_write2_b32 v93, v113, v119 offset0:88 offset1:124
	ds_write2_b32 v94, v115, v121 offset0:152 offset1:188
	s_branch .LBB0_756

.LBB0_778:
	v_cndmask_b32_e64 v28, 0, 1, s[12:13]
	v_cmp_ne_u32_e64 s[8:9], 1, v28
	s_andn2_b64 vcc, exec, s[12:13]
	s_cbranch_vccnz .LBB0_782
	v_lshlrev_b32_e32 v28, 16, v74
	v_add_f32_e32 v28, 0, v28
	v_lshlrev_b32_e32 v29, 16, v75
	v_exp_f32_e32 v41, v28
	v_cvt_f32_u32_e32 v35, v1
	v_cvt_f32_u32_e32 v34, v8
	v_add_f32_e32 v29, v28, v29
	v_lshlrev_b32_e32 v30, 16, v76
	v_add_f32_e32 v40, v29, v30
	v_lshlrev_b32_e32 v30, 16, v77
	v_lshlrev_b32_e32 v33, 16, v13
	v_lshlrev_b32_e32 v32, 16, v12
	v_add_f32_e32 v98, v40, v30
	v_lshlrev_b32_e32 v30, 16, v63
	v_mul_f32_e32 v36, v4, v32
	v_mul_f32_e32 v37, v5, v33
	v_cvt_f32_u32_e32 v121, v9
	v_cvt_f32_u32_e32 v120, v0
	v_mul_f32_e32 v99, v41, v30
	v_mul_f32_e32 v30, s10, v34
	v_mul_f32_e32 v31, s10, v35
	v_mul_f32_e32 v38, v36, v2
	v_mul_f32_e32 v39, v37, v3
	v_exp_f32_e32 v115, v29
	v_rcp_f32_e32 v28, v41
	v_mul_f32_e32 v30, v30, v38
	v_mul_f32_e32 v31, v31, v39
	v_mul_f32_e32 v39, v41, v39
	v_lshlrev_b32_e32 v41, 16, v15
	v_exp_f32_e32 v124, v40
	v_lshlrev_b32_e32 v40, 16, v14
	v_mul_f32_e32 v116, v4, v40
	v_mul_f32_e32 v117, v5, v41
	v_lshlrev_b32_e32 v106, 16, v66
	v_mul_f32_e32 v36, s10, v120
	v_mul_f32_e32 v37, s10, v121
	v_mul_f32_e32 v122, v116, v10
	v_mul_f32_e32 v123, v117, v11
	v_rcp_f32_e32 v29, v115
	v_mul_f32_e32 v106, v115, v106
	v_mul_f32_e32 v115, v115, v122
	v_mul_f32_e32 v36, v36, v122
	v_mul_f32_e32 v37, v37, v123
	v_exp_f32_e32 v122, v98
	v_fma_f32 v34, v34, s10, -1.0
	v_fma_f32 v35, v35, s10, -1.0
	v_fma_f32 v120, v120, s10, -1.0
	v_fma_f32 v121, v121, s10, -1.0
	v_fma_f32 v34, v6, v34, 1.0
	v_fma_f32 v35, v7, v35, 1.0
	v_fma_f32 v120, v6, v120, 1.0
	v_fma_f32 v121, v7, v121, 1.0
	v_mul_f32_e32 v32, v34, v32
	v_mul_f32_e32 v33, v35, v33
	v_lshlrev_b32_e32 v35, 16, v69
	v_rcp_f32_e32 v34, v124
	v_mul_f32_e32 v113, v124, v35
	v_rcp_f32_e32 v35, v122
	s_and_b32 s4, s11, 2
	v_lshlrev_b32_e32 v125, 16, v73
	v_mul_f32_e32 v40, v120, v40
	v_mul_f32_e32 v41, v121, v41
	s_mulk_i32 s4, 0x5f00
	v_mul_f32_e32 v102, v28, v30
	v_mul_f32_e32 v104, v28, v32
	v_mul_f32_e32 v107, v29, v31
	v_mul_f32_e32 v109, v29, v33
	v_mul_f32_e32 v117, v34, v36
	v_mul_f32_e32 v119, v34, v40
	v_mul_f32_e32 v121, v124, v123
	v_mul_f32_e32 v122, v122, v125
	v_mul_f32_e32 v123, v35, v37
	v_mul_f32_e32 v125, v35, v41
	s_add_i32 s12, s4, 0
	v_mov_b32_dpp v100, v99 quad_perm:[1,1,3,3] row_mask:0xf bank_mask:0xf bound_ctrl:1
	v_mov_b32_dpp v101, v38 quad_perm:[1,1,3,3] row_mask:0xf bank_mask:0xf bound_ctrl:1
	v_mov_b32_dpp v103, v102 quad_perm:[1,1,3,3] row_mask:0xf bank_mask:0xf bound_ctrl:1
	v_mov_b32_dpp v105, v104 quad_perm:[1,1,3,3] row_mask:0xf bank_mask:0xf bound_ctrl:1
	v_mov_b32_dpp v108, v39 quad_perm:[1,1,3,3] row_mask:0xf bank_mask:0xf bound_ctrl:1
	v_mov_b32_dpp v110, v106 quad_perm:[1,1,3,3] row_mask:0xf bank_mask:0xf bound_ctrl:1
	v_mov_b32_dpp v111, v107 quad_perm:[1,1,3,3] row_mask:0xf bank_mask:0xf bound_ctrl:1
	v_mov_b32_dpp v112, v109 quad_perm:[1,1,3,3] row_mask:0xf bank_mask:0xf bound_ctrl:1
	v_mov_b32_dpp v114, v113 quad_perm:[1,1,3,3] row_mask:0xf bank_mask:0xf bound_ctrl:1
	v_mov_b32_dpp v116, v115 quad_perm:[1,1,3,3] row_mask:0xf bank_mask:0xf bound_ctrl:1
	v_mov_b32_dpp v118, v117 quad_perm:[1,1,3,3] row_mask:0xf bank_mask:0xf bound_ctrl:1
	v_mov_b32_dpp v120, v119 quad_perm:[1,1,3,3] row_mask:0xf bank_mask:0xf bound_ctrl:1
	v_mov_b32_dpp v124, v121 quad_perm:[1,1,3,3] row_mask:0xf bank_mask:0xf bound_ctrl:1
	v_mov_b32_dpp v126, v122 quad_perm:[1,1,3,3] row_mask:0xf bank_mask:0xf bound_ctrl:1
	v_mov_b32_dpp v127, v123 quad_perm:[1,1,3,3] row_mask:0xf bank_mask:0xf bound_ctrl:1
	v_mov_b32_dpp v129, v125 quad_perm:[1,1,3,3] row_mask:0xf bank_mask:0xf bound_ctrl:1
	s_and_saveexec_b64 s[4:5], s[6:7]
	s_cbranch_execz .LBB0_781
	v_cvt_pk_bf16_f32 v39, v39, v108
	v_cvt_pk_bf16_f32 v99, v99, v100
	v_cvt_pk_bf16_f32 v38, v38, v101
	v_lshl_add_u32 v100, v56, 1, s12
	v_cvt_pk_bf16_f32 v106, v106, v110
	ds_write2_b32 v100, v38, v39 offset1:36
	v_add_u32_e32 v38, 0x800, v100
	v_cvt_pk_bf16_f32 v109, v109, v112
	v_cvt_pk_bf16_f32 v107, v107, v111
	v_cvt_pk_bf16_f32 v104, v104, v105
	v_cvt_pk_bf16_f32 v102, v102, v103
	ds_write2_b32 v38, v99, v106 offset0:64 offset1:100
	v_add_u32_e32 v39, 0x1000, v100
	v_add_u32_e32 v99, 0x1800, v100
	v_cvt_pk_bf16_f32 v125, v125, v129
	v_cvt_pk_bf16_f32 v123, v123, v127
	v_cvt_pk_bf16_f32 v122, v122, v126
	v_cvt_pk_bf16_f32 v121, v121, v124
	v_cvt_pk_bf16_f32 v119, v119, v120
	v_cvt_pk_bf16_f32 v117, v117, v118
	v_cvt_pk_bf16_f32 v113, v113, v114
	v_cvt_pk_bf16_f32 v114, v115, v116
	ds_write2_b32 v39, v102, v107 offset0:128 offset1:164
	ds_write2_b32 v99, v104, v109 offset0:192 offset1:228
	ds_write2_b32 v100, v114, v121 offset0:72 offset1:108
	ds_write2_b32 v38, v113, v122 offset0:136 offset1:172
	ds_write2_b32 v39, v117, v123 offset0:200 offset1:236
	v_add_u32_e32 v38, 0x1c00, v100
	ds_write2_b32 v38, v119, v125 offset0:8 offset1:44
.LBB0_781:
	s_or_b64 exec, exec, s[4:5]
	v_lshlrev_b32_e32 v38, 16, v43
	v_add_f32_e32 v38, v98, v38
	v_lshlrev_b32_e32 v39, 16, v44
	v_add_f32_e32 v38, v38, v39
	v_lshlrev_b32_e32 v39, 16, v45
	v_add_f32_e32 v38, v38, v39
	v_lshlrev_b32_e32 v39, 16, v46
	v_add_f32_e32 v38, v38, v39
	v_lshlrev_b32_e32 v39, 16, v47
	v_add_f32_e32 v38, v38, v39
	v_lshlrev_b32_e32 v39, 16, v48
	v_add_f32_e32 v38, v38, v39
	v_lshlrev_b32_e32 v39, 16, v49
	v_add_f32_e32 v38, v38, v39
	v_lshlrev_b32_e32 v39, 16, v50
	v_add_f32_e32 v38, v38, v39
	v_lshlrev_b32_e32 v39, 16, v51
	v_add_f32_e32 v38, v38, v39
	v_lshlrev_b32_e32 v39, 16, v52
	v_add_f32_e32 v38, v38, v39
	v_lshlrev_b32_e32 v39, 16, v53
	v_add_f32_e32 v38, v38, v39
	v_lshlrev_b32_e32 v39, 16, v54
	v_add_f32_e32 v38, v38, v39
	v_exp_f32_e32 v38, v38
	s_nop 0
	v_mul_f32_e32 v34, v34, v38
	v_mul_f32_e32 v35, v35, v38
	v_mul_f32_e32 v28, v28, v38
	v_mul_f32_e32 v29, v29, v38
	v_mul_f32_e32 v40, v34, v40
	v_mul_f32_e32 v41, v35, v41
	v_mul_f32_e64 v34, v34, -v36
	v_mul_f32_e64 v35, v35, -v37
	v_mul_f32_e32 v32, v28, v32
	v_mul_f32_e32 v33, v29, v33
	v_mul_f32_e64 v28, v28, -v30
	v_mul_f32_e64 v29, v29, -v31
	v_add_u32_e32 v36, s12, v57
	v_cvt_pk_bf16_f32 v28, v28, v29
	v_cvt_pk_bf16_f32 v29, v34, v35
	v_cvt_pk_bf16_f32 v30, v32, v33
	v_cvt_pk_bf16_f32 v31, v40, v41
	v_add_u32_e32 v32, 0x2000, v36
	ds_write2_b64 v32, v[28:29], v[30:31] offset0:128 offset1:132
	v_lshl_or_b32 v28, v79, 16, v78
	v_lshl_or_b32 v29, v82, 16, v80
	v_add3_u32 v30, s12, v58, v59
	ds_write_b64 v30, v[28:29] offset:14336
	v_add_u32_e32 v28, s12, v61
	v_lshlrev_b32_e32 v29, 2, v60
	v_lshlrev_b32_e32 v30, 2, v55
	v_add3_u32 v28, v28, v29, v30
	ds_write_b32 v28, v38 offset:24064

.LBB0_784:
	s_and_b64 vcc, exec, s[8:9]
	s_cbranch_vccnz .LBB0_775
	v_lshlrev_b32_e32 v28, 16, v86
	v_add_f32_e32 v28, 0, v28
	v_lshlrev_b32_e32 v29, 16, v87
	v_exp_f32_e32 v41, v28
	v_cvt_f32_u32_e32 v35, v21
	v_cvt_f32_u32_e32 v34, v20
	v_add_f32_e32 v29, v28, v29
	v_lshlrev_b32_e32 v30, 16, v88
	v_add_f32_e32 v40, v29, v30
	v_lshlrev_b32_e32 v30, 16, v89
	v_lshlrev_b32_e32 v33, 16, v25
	v_lshlrev_b32_e32 v32, 16, v24
	v_add_f32_e32 v98, v40, v30
	v_lshlrev_b32_e32 v30, 16, v90
	v_mul_f32_e32 v36, v4, v32
	v_mul_f32_e32 v37, v5, v33
	v_cvt_f32_u32_e32 v121, v23
	v_cvt_f32_u32_e32 v120, v22
	v_mul_f32_e32 v99, v41, v30
	v_mul_f32_e32 v30, s10, v34
	v_mul_f32_e32 v31, s10, v35
	v_mul_f32_e32 v38, v16, v36
	v_mul_f32_e32 v39, v17, v37
	v_exp_f32_e32 v115, v29
	v_rcp_f32_e32 v28, v41
	v_mul_f32_e32 v30, v30, v38
	v_mul_f32_e32 v31, v31, v39
	v_mul_f32_e32 v39, v39, v41
	v_lshlrev_b32_e32 v41, 16, v27
	v_exp_f32_e32 v124, v40
	v_lshlrev_b32_e32 v40, 16, v26
	v_mul_f32_e32 v116, v4, v40
	v_mul_f32_e32 v117, v5, v41
	v_lshlrev_b32_e32 v106, 16, v91
	v_mul_f32_e32 v36, s10, v120
	v_mul_f32_e32 v37, s10, v121
	v_mul_f32_e32 v122, v18, v116
	v_mul_f32_e32 v123, v19, v117
	v_rcp_f32_e32 v29, v115
	v_mul_f32_e32 v106, v115, v106
	v_mul_f32_e32 v115, v122, v115
	v_mul_f32_e32 v36, v36, v122
	v_mul_f32_e32 v37, v37, v123
	v_exp_f32_e32 v122, v98
	v_fma_f32 v34, v34, s10, -1.0
	v_fma_f32 v35, v35, s10, -1.0
	v_fma_f32 v120, v120, s10, -1.0
	v_fma_f32 v121, v121, s10, -1.0
	v_fma_f32 v34, v6, v34, 1.0
	v_fma_f32 v35, v7, v35, 1.0
	v_fma_f32 v120, v6, v120, 1.0
	v_fma_f32 v121, v7, v121, 1.0
	v_mul_f32_e32 v32, v34, v32
	v_mul_f32_e32 v33, v35, v33
	v_lshlrev_b32_e32 v35, 16, v92
	v_rcp_f32_e32 v34, v124
	v_mul_f32_e32 v113, v124, v35
	v_rcp_f32_e32 v35, v122
	s_and_b32 s4, s14, 3
	v_lshlrev_b32_e32 v125, 16, v93
	v_mul_f32_e32 v40, v120, v40
	v_mul_f32_e32 v41, v121, v41
	s_mulk_i32 s4, 0x5f00
	v_mul_f32_e32 v102, v30, v28
	v_mul_f32_e32 v104, v32, v28
	v_mul_f32_e32 v107, v31, v29
	v_mul_f32_e32 v109, v33, v29
	v_mul_f32_e32 v117, v36, v34
	v_mul_f32_e32 v119, v40, v34
	v_mul_f32_e32 v121, v123, v124
	v_mul_f32_e32 v122, v122, v125
	v_mul_f32_e32 v123, v37, v35
	v_mul_f32_e32 v125, v41, v35
	s_add_i32 s8, s4, 0
	v_mov_b32_dpp v100, v99 quad_perm:[1,1,3,3] row_mask:0xf bank_mask:0xf bound_ctrl:1
	v_mov_b32_dpp v101, v38 quad_perm:[1,1,3,3] row_mask:0xf bank_mask:0xf bound_ctrl:1
	v_mov_b32_dpp v103, v102 quad_perm:[1,1,3,3] row_mask:0xf bank_mask:0xf bound_ctrl:1
	v_mov_b32_dpp v105, v104 quad_perm:[1,1,3,3] row_mask:0xf bank_mask:0xf bound_ctrl:1
	v_mov_b32_dpp v108, v39 quad_perm:[1,1,3,3] row_mask:0xf bank_mask:0xf bound_ctrl:1
	v_mov_b32_dpp v110, v106 quad_perm:[1,1,3,3] row_mask:0xf bank_mask:0xf bound_ctrl:1
	v_mov_b32_dpp v111, v107 quad_perm:[1,1,3,3] row_mask:0xf bank_mask:0xf bound_ctrl:1
	v_mov_b32_dpp v112, v109 quad_perm:[1,1,3,3] row_mask:0xf bank_mask:0xf bound_ctrl:1
	v_mov_b32_dpp v114, v113 quad_perm:[1,1,3,3] row_mask:0xf bank_mask:0xf bound_ctrl:1
	v_mov_b32_dpp v116, v115 quad_perm:[1,1,3,3] row_mask:0xf bank_mask:0xf bound_ctrl:1
	v_mov_b32_dpp v118, v117 quad_perm:[1,1,3,3] row_mask:0xf bank_mask:0xf bound_ctrl:1
	v_mov_b32_dpp v120, v119 quad_perm:[1,1,3,3] row_mask:0xf bank_mask:0xf bound_ctrl:1
	v_mov_b32_dpp v124, v121 quad_perm:[1,1,3,3] row_mask:0xf bank_mask:0xf bound_ctrl:1
	v_mov_b32_dpp v126, v122 quad_perm:[1,1,3,3] row_mask:0xf bank_mask:0xf bound_ctrl:1
	v_mov_b32_dpp v127, v123 quad_perm:[1,1,3,3] row_mask:0xf bank_mask:0xf bound_ctrl:1
	v_mov_b32_dpp v129, v125 quad_perm:[1,1,3,3] row_mask:0xf bank_mask:0xf bound_ctrl:1
	s_and_saveexec_b64 s[4:5], s[6:7]
	s_cbranch_execz .LBB0_774
	v_cvt_pk_bf16_f32 v39, v39, v108
	v_cvt_pk_bf16_f32 v99, v99, v100
	v_cvt_pk_bf16_f32 v38, v38, v101
	v_lshl_add_u32 v100, v56, 1, s8
	v_cvt_pk_bf16_f32 v106, v106, v110
	ds_write2_b32 v100, v38, v39 offset1:36
	v_add_u32_e32 v38, 0x800, v100
	v_cvt_pk_bf16_f32 v109, v109, v112
	v_cvt_pk_bf16_f32 v107, v107, v111
	v_cvt_pk_bf16_f32 v104, v104, v105
	v_cvt_pk_bf16_f32 v102, v102, v103
	ds_write2_b32 v38, v99, v106 offset0:64 offset1:100
	v_add_u32_e32 v39, 0x1000, v100
	v_add_u32_e32 v99, 0x1800, v100
	v_cvt_pk_bf16_f32 v125, v125, v129
	v_cvt_pk_bf16_f32 v123, v123, v127
	v_cvt_pk_bf16_f32 v122, v122, v126
	v_cvt_pk_bf16_f32 v121, v121, v124
	v_cvt_pk_bf16_f32 v119, v119, v120
	v_cvt_pk_bf16_f32 v117, v117, v118
	v_cvt_pk_bf16_f32 v113, v113, v114
	v_cvt_pk_bf16_f32 v114, v115, v116
	ds_write2_b32 v39, v102, v107 offset0:128 offset1:164
	ds_write2_b32 v99, v104, v109 offset0:192 offset1:228
	ds_write2_b32 v100, v114, v121 offset0:72 offset1:108
	ds_write2_b32 v38, v113, v122 offset0:136 offset1:172
	ds_write2_b32 v39, v117, v123 offset0:200 offset1:236
	v_add_u32_e32 v38, 0x1c00, v100
	ds_write2_b32 v38, v119, v125 offset0:8 offset1:44
	s_branch .LBB0_774
